# EpiResid: 16 xb row loads issued up front with counted vmcnt instead of load+vmcnt0 per piece
# speedup vs baseline: 1.0210x; 1.0088x over previous
; __device__ __forceinline__ u32x4 pack8(const f32x4& a, const f32x4& b) { u32x4 w; w.x = pk2(a[0], a[1]); w.y = pk2(a[2], a[3]); w.z = pk2(b[0], b[1]); w.w = pk2(b[2], b[3]); return w; }
;     __device__ __forceinline__ void operator()(const f32x4 (&acc)[2][2][4][2], const pg8::Unit& u, int wr, int wc, int fr, int fq) const { asm volatile("" : "+v"(fr), "+v"(fq));
; #pragma unroll
;         for (int am_ = 0; am_ < 8; ++am_) { const int ai = am_ >> 2, m = am_ & 3; const int row = u.pm * 256 + ai * 128 + wr * 64 + m * 16 + fr; float sq = 0.f;
; #pragma unroll
;             for (int bj = 0; bj < 2; ++bj) { const int col0 = u.pn * 256 + bj * 128 + wc * 32 + 8 * fq; bf16_t* xp = xb + (size_t)row * D + col0; const u32x4 o = *(const u32x4*)xp;
;                 f32x4 x0 = {bflo(o.x), bfhi(o.x), bflo(o.y), bfhi(o.y)}, x1 = {bflo(o.z), bfhi(o.z), bflo(o.w), bfhi(o.w)}; x0 += acc[ai][bj][m][0] * scale; x1 += acc[ai][bj][m][1] * scale;
;                 *(u32x4*)xp = pack8(x0, x1);
;                 sq += (x0[0] * x0[0] + x0[1] * x0[1]) + (x0[2] * x0[2] + x0[3] * x0[3]) + (x1[0] * x1[0] + x1[1] * x1[1]) + (x1[2] * x1[2] + x1[3] * x1[3]); }
;             sq += __shfl_xor(sq, 16); sq += __shfl_xor(sq, 32);
;             if (fq == 0) ssn[(size_t)row * 16 + u.pn * 4 + wc] = sq; }
.LBB0_1585:
	v_and_b32_e32 v145, 64, v166
	v_xor_b32_e32 v143, 16, v166
	v_add_u32_e32 v145, 64, v145
	s_lshl_b32 s33, s79, 8
	v_cmp_lt_i32_e32 vcc, v143, v145
	v_mov_b32_e32 v139, v148
	v_mov_b32_e32 v142, v149
	s_add_i32 s33, s33, s46
	v_cndmask_b32_e32 v143, v166, v143, vcc
	v_lshlrev_b32_e32 v153, 2, v143
	v_add_u32_e32 v144, s33, v142
	s_lshl_b32 s33, s78, 8
	v_xor_b32_e32 v143, 32, v166
	s_or_b32 s33, s33, s47
	v_cmp_lt_i32_e32 vcc, v143, v145
	v_ashrrev_i32_e32 v145, 31, v144
	v_lshl_add_u32 v142, v139, 3, s33
	v_cndmask_b32_e32 v143, v166, v143, vcc
	v_lshlrev_b64 v[146:147], 11, v[144:145]
	v_lshlrev_b32_e32 v152, 2, v143
	v_lshl_add_u64 v[146:147], s[86:87], 0, v[146:147]
	v_ashrrev_i32_e32 v143, 31, v142
	v_lshl_add_u64 v[146:147], v[142:143], 1, v[146:147]
	global_load_dwordx4 v[172:175], v[146:147], off
	global_load_dwordx4 v[176:179], v[146:147], off offset:256
	s_mov_b64 s[100:101], 0x8000
	v_lshl_add_u64 v[162:163], v[146:147], 0, s[100:101]
	global_load_dwordx4 v[180:183], v[162:163], off
	global_load_dwordx4 v[184:187], v[162:163], off offset:256
	v_lshl_add_u64 v[164:165], v[162:163], 0, s[100:101]
	global_load_dwordx4 v[188:191], v[164:165], off
	global_load_dwordx4 v[192:195], v[164:165], off offset:256
	v_lshl_add_u64 v[162:163], v[164:165], 0, s[100:101]
	global_load_dwordx4 v[196:199], v[162:163], off
	global_load_dwordx4 v[200:203], v[162:163], off offset:256
	s_mov_b64 s[100:101], 0x28000
	v_lshl_add_u64 v[164:165], v[162:163], 0, s[100:101]
	global_load_dwordx4 v[204:207], v[164:165], off
	global_load_dwordx4 v[208:211], v[164:165], off offset:256
	s_mov_b64 s[100:101], 0x8000
	v_lshl_add_u64 v[162:163], v[164:165], 0, s[100:101]
	global_load_dwordx4 v[212:215], v[162:163], off
	global_load_dwordx4 v[216:219], v[162:163], off offset:256
	v_lshl_add_u64 v[164:165], v[162:163], 0, s[100:101]
	global_load_dwordx4 v[220:223], v[164:165], off
	global_load_dwordx4 v[224:227], v[164:165], off offset:256
	v_lshl_add_u64 v[162:163], v[164:165], 0, s[100:101]
	global_load_dwordx4 v[234:237], v[162:163], off
	global_load_dwordx4 v[238:241], v[162:163], off offset:256
	v_cmp_eq_u32_e32 vcc, 0, v139
	s_lshl_b32 s38, s78, 2
	s_ashr_i32 s39, s38, 31
	s_waitcnt vmcnt(15)
	v_mov_b32_e32 v154, v172
	v_mov_b32_e32 v155, v173
	v_mov_b32_e32 v156, v174
	v_mov_b32_e32 v157, v175
	v_lshlrev_b32_e32 v158, 16, v154
	v_and_b32_e32 v159, 0xffff0000, v154
	v_lshlrev_b32_e32 v154, 16, v155
	v_and_b32_e32 v155, 0xffff0000, v155
	v_lshlrev_b32_e32 v160, 16, v156
	v_and_b32_e32 v161, 0xffff0000, v156
	v_lshlrev_b32_e32 v156, 16, v157
	v_and_b32_e32 v157, 0xffff0000, v157
	v_pk_fma_f32 v[154:155], s[26:27], v[122:123], v[154:155]
	v_pk_fma_f32 v[158:159], s[6:7], v[120:121], v[158:159]
	v_pk_fma_f32 v[126:127], s[26:27], v[126:127], v[156:157]
	v_pk_fma_f32 v[124:125], s[6:7], v[124:125], v[160:161]
	v_cvt_pk_bf16_f32 v120, v158, v159
	v_cvt_pk_bf16_f32 v121, v154, v155
	v_cvt_pk_bf16_f32 v122, v124, v125
	v_cvt_pk_bf16_f32 v123, v126, v127
	global_store_dwordx4 v[146:147], v[120:123], off
	s_nop 1
	v_mul_f32_e32 v120, v159, v159
	v_mul_f32_e32 v121, v155, v155
	v_fmac_f32_e32 v120, v158, v158
	v_fmac_f32_e32 v121, v154, v154
	v_add_f32_e32 v120, v120, v121
	v_mul_f32_e32 v121, v125, v125
	v_fmac_f32_e32 v121, v124, v124
	v_add_f32_e32 v120, v121, v120
	v_mul_f32_e32 v121, v127, v127
	v_fmac_f32_e32 v121, v126, v126
	v_add_f32_e32 v139, v121, v120
	s_waitcnt vmcnt(15)
	v_mov_b32_e32 v120, v176
	v_mov_b32_e32 v121, v177
	v_mov_b32_e32 v122, v178
	v_mov_b32_e32 v123, v179
	v_lshlrev_b32_e32 v124, 16, v120
	v_and_b32_e32 v125, 0xffff0000, v120
	v_lshlrev_b32_e32 v120, 16, v121
	v_and_b32_e32 v121, 0xffff0000, v121
	v_lshlrev_b32_e32 v126, 16, v122
	v_and_b32_e32 v127, 0xffff0000, v122
	v_lshlrev_b32_e32 v122, 16, v123
	v_and_b32_e32 v123, 0xffff0000, v123
	v_pk_fma_f32 v[118:119], s[26:27], v[118:119], v[120:121]
	v_pk_fma_f32 v[116:117], s[6:7], v[116:117], v[124:125]
	v_pk_fma_f32 v[120:121], s[26:27], v[114:115], v[122:123]
	v_pk_fma_f32 v[122:123], s[6:7], v[112:113], v[126:127]
	v_cvt_pk_bf16_f32 v112, v116, v117
	v_cvt_pk_bf16_f32 v113, v118, v119
	v_cvt_pk_bf16_f32 v114, v122, v123
	v_cvt_pk_bf16_f32 v115, v120, v121
	global_store_dwordx4 v[146:147], v[112:115], off offset:256
	s_nop 1
	v_mul_f32_e32 v112, v117, v117
	v_mul_f32_e32 v113, v119, v119
	v_fmac_f32_e32 v112, v116, v116
	v_fmac_f32_e32 v113, v118, v118
	v_add_f32_e32 v112, v112, v113
	v_mul_f32_e32 v113, v123, v123
	v_fmac_f32_e32 v113, v122, v122
	v_add_f32_e32 v112, v113, v112
	v_mul_f32_e32 v113, v121, v121
	v_fmac_f32_e32 v113, v120, v120
	v_add_f32_e32 v112, v113, v112
	v_add_f32_e32 v112, v139, v112
	ds_bpermute_b32 v113, v153, v112
	s_waitcnt lgkmcnt(0)
	v_add_f32_e32 v112, v112, v113
	ds_bpermute_b32 v113, v152, v112
	s_and_saveexec_b64 s[40:41], vcc
	s_cbranch_execz .LBB0_1587
	v_lshlrev_b64 v[114:115], 6, v[144:145]
	v_lshl_add_u64 v[114:115], s[20:21], 0, v[114:115]
	v_lshl_add_u64 v[114:115], s[38:39], 2, v[114:115]
	s_lshl_b32 s78, s44, 2
	s_mov_b32 s79, s31
	v_lshl_add_u64 v[114:115], v[114:115], 0, s[78:79]
	s_waitcnt lgkmcnt(0)
	v_add_f32_e32 v112, v112, v113
	global_store_dword v[114:115], v112, off
; __device__ __forceinline__ u32x4 pack8(const f32x4& a, const f32x4& b) { u32x4 w; w.x = pk2(a[0], a[1]); w.y = pk2(a[2], a[3]); w.z = pk2(b[0], b[1]); w.w = pk2(b[2], b[3]); return w; }
;     __device__ __forceinline__ void operator()(const f32x4 (&acc)[2][2][4][2], const pg8::Unit& u, int wr, int wc, int fr, int fq) const { asm volatile("" : "+v"(fr), "+v"(fq));
;     ...
;         for (int am_ = 0; am_ < 8; ++am_) { const int ai = am_ >> 2, m = am_ & 3; const int row = u.pm * 256 + ai * 128 + wr * 64 + m * 16 + fr; float sq = 0.f;
; #pragma unroll
;             for (int bj = 0; bj < 2; ++bj) { const int col0 = u.pn * 256 + bj * 128 + wc * 32 + 8 * fq; bf16_t* xp = xb + (size_t)row * D + col0; const u32x4 o = *(const u32x4*)xp;
;                 f32x4 x0 = {bflo(o.x), bfhi(o.x), bflo(o.y), bfhi(o.y)}, x1 = {bflo(o.z), bfhi(o.z), bflo(o.w), bfhi(o.w)}; x0 += acc[ai][bj][m][0] * scale; x1 += acc[ai][bj][m][1] * scale;
;                 *(u32x4*)xp = pack8(x0, x1);
;                 sq += (x0[0] * x0[0] + x0[1] * x0[1]) + (x0[2] * x0[2] + x0[3] * x0[3]) + (x1[0] * x1[0] + x1[1] * x1[1]) + (x1[2] * x1[2] + x1[3] * x1[3]); }
;             sq += __shfl_xor(sq, 16); sq += __shfl_xor(sq, 32);
;             if (fq == 0) ssn[(size_t)row * 16 + u.pn * 4 + wc] = sq; }
.LBB0_1587:
	s_or_b64 exec, exec, s[40:41]
	v_add_u32_e32 v112, 16, v144
	s_waitcnt lgkmcnt(0)
	v_ashrrev_i32_e32 v113, 31, v112
	v_lshlrev_b64 v[114:115], 11, v[112:113]
	v_lshl_add_u64 v[114:115], s[86:87], 0, v[114:115]
	v_lshl_add_u64 v[118:119], v[142:143], 1, v[114:115]
	s_waitcnt vmcnt(15)
	v_mov_b32_e32 v114, v180
	v_mov_b32_e32 v115, v181
	v_mov_b32_e32 v116, v182
	v_mov_b32_e32 v117, v183
	v_lshlrev_b32_e32 v120, 16, v114
	v_and_b32_e32 v121, 0xffff0000, v114
	v_lshlrev_b32_e32 v114, 16, v115
	v_and_b32_e32 v115, 0xffff0000, v115
	v_lshlrev_b32_e32 v122, 16, v116
	v_and_b32_e32 v123, 0xffff0000, v116
	v_lshlrev_b32_e32 v116, 16, v117
	v_and_b32_e32 v117, 0xffff0000, v117
	v_pk_fma_f32 v[110:111], s[26:27], v[110:111], v[114:115]
	v_pk_fma_f32 v[108:109], s[6:7], v[108:109], v[120:121]
	v_pk_fma_f32 v[114:115], s[26:27], v[106:107], v[116:117]
	v_pk_fma_f32 v[116:117], s[6:7], v[104:105], v[122:123]
	v_cvt_pk_bf16_f32 v104, v108, v109
	v_cvt_pk_bf16_f32 v105, v110, v111
	v_cvt_pk_bf16_f32 v106, v116, v117
	v_cvt_pk_bf16_f32 v107, v114, v115
	global_store_dwordx4 v[118:119], v[104:107], off
	s_nop 1
	v_mul_f32_e32 v104, v109, v109
	v_mul_f32_e32 v105, v111, v111
	v_fmac_f32_e32 v104, v108, v108
	v_fmac_f32_e32 v105, v110, v110
	v_add_f32_e32 v104, v104, v105
	v_mul_f32_e32 v105, v117, v117
	v_fmac_f32_e32 v105, v116, v116
	v_add_f32_e32 v104, v105, v104
	v_mul_f32_e32 v105, v115, v115
	v_fmac_f32_e32 v105, v114, v114
	v_add_f32_e32 v114, v105, v104
	s_waitcnt vmcnt(15)
	v_mov_b32_e32 v104, v184
	v_mov_b32_e32 v105, v185
	v_mov_b32_e32 v106, v186
	v_mov_b32_e32 v107, v187
	v_lshlrev_b32_e32 v108, 16, v104
	v_and_b32_e32 v109, 0xffff0000, v104
	v_lshlrev_b32_e32 v104, 16, v105
	v_and_b32_e32 v105, 0xffff0000, v105
	v_lshlrev_b32_e32 v110, 16, v106
	v_and_b32_e32 v111, 0xffff0000, v106
	v_lshlrev_b32_e32 v106, 16, v107
	v_and_b32_e32 v107, 0xffff0000, v107
	v_pk_fma_f32 v[102:103], s[26:27], v[102:103], v[104:105]
	v_pk_fma_f32 v[100:101], s[6:7], v[100:101], v[108:109]
	v_pk_fma_f32 v[104:105], s[26:27], v[98:99], v[106:107]
	v_pk_fma_f32 v[106:107], s[6:7], v[96:97], v[110:111]
	v_cvt_pk_bf16_f32 v96, v100, v101
	v_cvt_pk_bf16_f32 v97, v102, v103
	v_cvt_pk_bf16_f32 v98, v106, v107
	v_cvt_pk_bf16_f32 v99, v104, v105
	global_store_dwordx4 v[118:119], v[96:99], off offset:256
	s_nop 1
	v_mul_f32_e32 v96, v101, v101
	v_mul_f32_e32 v97, v103, v103
	v_fmac_f32_e32 v96, v100, v100
	v_fmac_f32_e32 v97, v102, v102
	v_add_f32_e32 v96, v96, v97
	v_mul_f32_e32 v97, v107, v107
	v_fmac_f32_e32 v97, v106, v106
	v_add_f32_e32 v96, v97, v96
	v_mul_f32_e32 v97, v105, v105
	v_fmac_f32_e32 v97, v104, v104
	v_add_f32_e32 v96, v97, v96
	v_add_f32_e32 v96, v114, v96
	ds_bpermute_b32 v97, v153, v96
	s_waitcnt lgkmcnt(0)
	v_add_f32_e32 v96, v96, v97
	ds_bpermute_b32 v97, v152, v96
	s_and_saveexec_b64 s[40:41], vcc
	s_cbranch_execz .LBB0_1589
	v_lshlrev_b64 v[98:99], 6, v[112:113]
	v_lshl_add_u64 v[98:99], s[20:21], 0, v[98:99]
	v_lshl_add_u64 v[98:99], s[38:39], 2, v[98:99]
	s_lshl_b32 s78, s44, 2
	s_mov_b32 s79, s31
	v_lshl_add_u64 v[98:99], v[98:99], 0, s[78:79]
	s_waitcnt lgkmcnt(0)
	v_add_f32_e32 v96, v96, v97
	global_store_dword v[98:99], v96, off
.LBB0_1589:
	s_or_b64 exec, exec, s[40:41]
	v_add_u32_e32 v96, 32, v144
	s_waitcnt lgkmcnt(0)
	v_ashrrev_i32_e32 v97, 31, v96
	v_lshlrev_b64 v[98:99], 11, v[96:97]
	v_lshl_add_u64 v[98:99], s[86:87], 0, v[98:99]
	v_lshl_add_u64 v[102:103], v[142:143], 1, v[98:99]
	s_waitcnt vmcnt(15)
	v_mov_b32_e32 v98, v188
	v_mov_b32_e32 v99, v189
	v_mov_b32_e32 v100, v190
	v_mov_b32_e32 v101, v191
	v_lshlrev_b32_e32 v104, 16, v98
	v_and_b32_e32 v105, 0xffff0000, v98
	v_lshlrev_b32_e32 v98, 16, v99
	v_and_b32_e32 v99, 0xffff0000, v99
	v_lshlrev_b32_e32 v106, 16, v100
	v_and_b32_e32 v107, 0xffff0000, v100
	v_lshlrev_b32_e32 v100, 16, v101
	v_and_b32_e32 v101, 0xffff0000, v101
	v_pk_fma_f32 v[94:95], s[26:27], v[94:95], v[98:99]
	v_pk_fma_f32 v[92:93], s[6:7], v[92:93], v[104:105]
	v_pk_fma_f32 v[98:99], s[26:27], v[90:91], v[100:101]
	v_pk_fma_f32 v[100:101], s[6:7], v[88:89], v[106:107]
	v_cvt_pk_bf16_f32 v88, v92, v93
	v_cvt_pk_bf16_f32 v89, v94, v95
	v_cvt_pk_bf16_f32 v90, v100, v101
	v_cvt_pk_bf16_f32 v91, v98, v99
	global_store_dwordx4 v[102:103], v[88:91], off
	s_nop 1
	v_mul_f32_e32 v88, v93, v93
	v_mul_f32_e32 v89, v95, v95
	v_fmac_f32_e32 v88, v92, v92
	v_fmac_f32_e32 v89, v94, v94
	v_add_f32_e32 v88, v88, v89
	v_mul_f32_e32 v89, v101, v101
	v_fmac_f32_e32 v89, v100, v100
	v_add_f32_e32 v88, v89, v88
	v_mul_f32_e32 v89, v99, v99
	v_fmac_f32_e32 v89, v98, v98
	v_add_f32_e32 v98, v89, v88
	s_waitcnt vmcnt(15)
	v_mov_b32_e32 v88, v192
	v_mov_b32_e32 v89, v193
	v_mov_b32_e32 v90, v194
	v_mov_b32_e32 v91, v195
	v_lshlrev_b32_e32 v92, 16, v88
	v_and_b32_e32 v93, 0xffff0000, v88
	v_lshlrev_b32_e32 v88, 16, v89
	v_and_b32_e32 v89, 0xffff0000, v89
	v_lshlrev_b32_e32 v94, 16, v90
	v_and_b32_e32 v95, 0xffff0000, v90
	v_lshlrev_b32_e32 v90, 16, v91
	v_and_b32_e32 v91, 0xffff0000, v91
	v_pk_fma_f32 v[86:87], s[26:27], v[86:87], v[88:89]
	v_pk_fma_f32 v[84:85], s[6:7], v[84:85], v[92:93]
	v_pk_fma_f32 v[88:89], s[26:27], v[82:83], v[90:91]
	v_pk_fma_f32 v[90:91], s[6:7], v[80:81], v[94:95]
	v_cvt_pk_bf16_f32 v80, v84, v85
	v_cvt_pk_bf16_f32 v81, v86, v87
	v_cvt_pk_bf16_f32 v82, v90, v91
	v_cvt_pk_bf16_f32 v83, v88, v89
	global_store_dwordx4 v[102:103], v[80:83], off offset:256
	s_nop 1
	v_mul_f32_e32 v80, v85, v85
	v_mul_f32_e32 v81, v87, v87
	v_fmac_f32_e32 v80, v84, v84
	v_fmac_f32_e32 v81, v86, v86
	v_add_f32_e32 v80, v80, v81
	v_mul_f32_e32 v81, v91, v91
	v_fmac_f32_e32 v81, v90, v90
	v_add_f32_e32 v80, v81, v80
	v_mul_f32_e32 v81, v89, v89
	v_fmac_f32_e32 v81, v88, v88
	v_add_f32_e32 v80, v81, v80
	v_add_f32_e32 v80, v98, v80
	ds_bpermute_b32 v81, v153, v80
	s_waitcnt lgkmcnt(0)
	v_add_f32_e32 v80, v80, v81
	ds_bpermute_b32 v81, v152, v80
	s_and_saveexec_b64 s[40:41], vcc
	s_cbranch_execz .LBB0_1591
	v_lshlrev_b64 v[82:83], 6, v[96:97]
	v_lshl_add_u64 v[82:83], s[20:21], 0, v[82:83]
	v_lshl_add_u64 v[82:83], s[38:39], 2, v[82:83]
	s_lshl_b32 s78, s44, 2
	s_mov_b32 s79, s31
	v_lshl_add_u64 v[82:83], v[82:83], 0, s[78:79]
	s_waitcnt lgkmcnt(0)
	v_add_f32_e32 v80, v80, v81
	global_store_dword v[82:83], v80, off
; __device__ __forceinline__ u32x4 pack8(const f32x4& a, const f32x4& b) { u32x4 w; w.x = pk2(a[0], a[1]); w.y = pk2(a[2], a[3]); w.z = pk2(b[0], b[1]); w.w = pk2(b[2], b[3]); return w; }
;     __device__ __forceinline__ void operator()(const f32x4 (&acc)[2][2][4][2], const pg8::Unit& u, int wr, int wc, int fr, int fq) const { asm volatile("" : "+v"(fr), "+v"(fq));
;     ...
;         for (int am_ = 0; am_ < 8; ++am_) { const int ai = am_ >> 2, m = am_ & 3; const int row = u.pm * 256 + ai * 128 + wr * 64 + m * 16 + fr; float sq = 0.f;
; #pragma unroll
;             for (int bj = 0; bj < 2; ++bj) { const int col0 = u.pn * 256 + bj * 128 + wc * 32 + 8 * fq; bf16_t* xp = xb + (size_t)row * D + col0; const u32x4 o = *(const u32x4*)xp;
;                 f32x4 x0 = {bflo(o.x), bfhi(o.x), bflo(o.y), bfhi(o.y)}, x1 = {bflo(o.z), bfhi(o.z), bflo(o.w), bfhi(o.w)}; x0 += acc[ai][bj][m][0] * scale; x1 += acc[ai][bj][m][1] * scale;
;                 *(u32x4*)xp = pack8(x0, x1);
;                 sq += (x0[0] * x0[0] + x0[1] * x0[1]) + (x0[2] * x0[2] + x0[3] * x0[3]) + (x1[0] * x1[0] + x1[1] * x1[1]) + (x1[2] * x1[2] + x1[3] * x1[3]); }
;             sq += __shfl_xor(sq, 16); sq += __shfl_xor(sq, 32);
;             if (fq == 0) ssn[(size_t)row * 16 + u.pn * 4 + wc] = sq; }
.LBB0_1591:
	s_or_b64 exec, exec, s[40:41]
	v_add_u32_e32 v80, 48, v144
	s_waitcnt lgkmcnt(0)
	v_ashrrev_i32_e32 v81, 31, v80
	v_lshlrev_b64 v[82:83], 11, v[80:81]
	v_lshl_add_u64 v[82:83], s[86:87], 0, v[82:83]
	v_lshl_add_u64 v[86:87], v[142:143], 1, v[82:83]
	s_waitcnt vmcnt(15)
	v_mov_b32_e32 v82, v196
	v_mov_b32_e32 v83, v197
	v_mov_b32_e32 v84, v198
	v_mov_b32_e32 v85, v199
	v_lshlrev_b32_e32 v88, 16, v82
	v_and_b32_e32 v89, 0xffff0000, v82
	v_lshlrev_b32_e32 v82, 16, v83
	v_and_b32_e32 v83, 0xffff0000, v83
	v_lshlrev_b32_e32 v90, 16, v84
	v_and_b32_e32 v91, 0xffff0000, v84
	v_lshlrev_b32_e32 v84, 16, v85
	v_and_b32_e32 v85, 0xffff0000, v85
	v_pk_fma_f32 v[78:79], s[26:27], v[78:79], v[82:83]
	v_pk_fma_f32 v[76:77], s[6:7], v[76:77], v[88:89]
	v_pk_fma_f32 v[82:83], s[26:27], v[74:75], v[84:85]
	v_pk_fma_f32 v[84:85], s[6:7], v[72:73], v[90:91]
	v_cvt_pk_bf16_f32 v72, v76, v77
	v_cvt_pk_bf16_f32 v73, v78, v79
	v_cvt_pk_bf16_f32 v74, v84, v85
	v_cvt_pk_bf16_f32 v75, v82, v83
	global_store_dwordx4 v[86:87], v[72:75], off
	s_nop 1
	v_mul_f32_e32 v72, v77, v77
	v_mul_f32_e32 v73, v79, v79
	v_fmac_f32_e32 v72, v76, v76
	v_fmac_f32_e32 v73, v78, v78
	v_add_f32_e32 v72, v72, v73
	v_mul_f32_e32 v73, v85, v85
	v_fmac_f32_e32 v73, v84, v84
	v_add_f32_e32 v72, v73, v72
	v_mul_f32_e32 v73, v83, v83
	v_fmac_f32_e32 v73, v82, v82
	v_add_f32_e32 v82, v73, v72
	s_waitcnt vmcnt(15)
	v_mov_b32_e32 v72, v200
	v_mov_b32_e32 v73, v201
	v_mov_b32_e32 v74, v202
	v_mov_b32_e32 v75, v203
	v_lshlrev_b32_e32 v76, 16, v72
	v_and_b32_e32 v77, 0xffff0000, v72
	v_lshlrev_b32_e32 v72, 16, v73
	v_and_b32_e32 v73, 0xffff0000, v73
	v_lshlrev_b32_e32 v78, 16, v74
	v_and_b32_e32 v79, 0xffff0000, v74
	v_lshlrev_b32_e32 v74, 16, v75
	v_and_b32_e32 v75, 0xffff0000, v75
	v_pk_fma_f32 v[70:71], s[26:27], v[70:71], v[72:73]
	v_pk_fma_f32 v[68:69], s[6:7], v[68:69], v[76:77]
	v_pk_fma_f32 v[72:73], s[26:27], v[66:67], v[74:75]
	v_pk_fma_f32 v[74:75], s[6:7], v[64:65], v[78:79]
	v_cvt_pk_bf16_f32 v64, v68, v69
	v_cvt_pk_bf16_f32 v65, v70, v71
	v_cvt_pk_bf16_f32 v66, v74, v75
	v_cvt_pk_bf16_f32 v67, v72, v73
	global_store_dwordx4 v[86:87], v[64:67], off offset:256
	s_nop 1
	v_mul_f32_e32 v64, v69, v69
	v_mul_f32_e32 v65, v71, v71
	v_fmac_f32_e32 v64, v68, v68
	v_fmac_f32_e32 v65, v70, v70
	v_add_f32_e32 v64, v64, v65
	v_mul_f32_e32 v65, v75, v75
	v_fmac_f32_e32 v65, v74, v74
	v_add_f32_e32 v64, v65, v64
	v_mul_f32_e32 v65, v73, v73
	v_fmac_f32_e32 v65, v72, v72
	v_add_f32_e32 v64, v65, v64
	v_add_f32_e32 v64, v82, v64
	ds_bpermute_b32 v65, v153, v64
	s_waitcnt lgkmcnt(0)
	v_add_f32_e32 v64, v64, v65
	ds_bpermute_b32 v65, v152, v64
	s_and_saveexec_b64 s[40:41], vcc
	s_cbranch_execz .LBB0_1593
	v_lshlrev_b64 v[66:67], 6, v[80:81]
	v_lshl_add_u64 v[66:67], s[20:21], 0, v[66:67]
	v_lshl_add_u64 v[66:67], s[38:39], 2, v[66:67]
	s_lshl_b32 s78, s44, 2
	s_mov_b32 s79, s31
	v_lshl_add_u64 v[66:67], v[66:67], 0, s[78:79]
	s_waitcnt lgkmcnt(0)
	v_add_f32_e32 v64, v64, v65
	global_store_dword v[66:67], v64, off
.LBB0_1593:
	s_or_b64 exec, exec, s[40:41]
	v_add_u32_e32 v64, 0x80, v144
	s_waitcnt lgkmcnt(0)
	v_ashrrev_i32_e32 v65, 31, v64
	v_lshlrev_b64 v[66:67], 11, v[64:65]
	v_lshl_add_u64 v[66:67], s[86:87], 0, v[66:67]
	v_lshl_add_u64 v[70:71], v[142:143], 1, v[66:67]
	s_waitcnt vmcnt(15)
	v_mov_b32_e32 v66, v204
	v_mov_b32_e32 v67, v205
	v_mov_b32_e32 v68, v206
	v_mov_b32_e32 v69, v207
	v_lshlrev_b32_e32 v72, 16, v66
	v_and_b32_e32 v73, 0xffff0000, v66
	v_lshlrev_b32_e32 v66, 16, v67
	v_and_b32_e32 v67, 0xffff0000, v67
	v_lshlrev_b32_e32 v74, 16, v68
	v_and_b32_e32 v75, 0xffff0000, v68
	v_lshlrev_b32_e32 v68, 16, v69
	v_and_b32_e32 v69, 0xffff0000, v69
	v_pk_fma_f32 v[62:63], s[26:27], v[62:63], v[66:67]
	v_pk_fma_f32 v[60:61], s[6:7], v[60:61], v[72:73]
	v_pk_fma_f32 v[66:67], s[26:27], v[58:59], v[68:69]
	v_pk_fma_f32 v[68:69], s[6:7], v[56:57], v[74:75]
	v_cvt_pk_bf16_f32 v56, v60, v61
	v_cvt_pk_bf16_f32 v57, v62, v63
	v_cvt_pk_bf16_f32 v58, v68, v69
	v_cvt_pk_bf16_f32 v59, v66, v67
	global_store_dwordx4 v[70:71], v[56:59], off
	s_nop 1
	v_mul_f32_e32 v56, v61, v61
	v_mul_f32_e32 v57, v63, v63
	v_fmac_f32_e32 v56, v60, v60
	v_fmac_f32_e32 v57, v62, v62
	v_add_f32_e32 v56, v56, v57
	v_mul_f32_e32 v57, v69, v69
	v_fmac_f32_e32 v57, v68, v68
	v_add_f32_e32 v56, v57, v56
	v_mul_f32_e32 v57, v67, v67
	v_fmac_f32_e32 v57, v66, v66
	v_add_f32_e32 v66, v57, v56
	s_waitcnt vmcnt(15)
	v_mov_b32_e32 v56, v208
	v_mov_b32_e32 v57, v209
	v_mov_b32_e32 v58, v210
	v_mov_b32_e32 v59, v211
	v_lshlrev_b32_e32 v60, 16, v56
	v_and_b32_e32 v61, 0xffff0000, v56
	v_lshlrev_b32_e32 v56, 16, v57
	v_and_b32_e32 v57, 0xffff0000, v57
	v_lshlrev_b32_e32 v62, 16, v58
	v_and_b32_e32 v63, 0xffff0000, v58
	v_lshlrev_b32_e32 v58, 16, v59
	v_and_b32_e32 v59, 0xffff0000, v59
	v_pk_fma_f32 v[54:55], s[26:27], v[54:55], v[56:57]
	v_pk_fma_f32 v[52:53], s[6:7], v[52:53], v[60:61]
	v_pk_fma_f32 v[56:57], s[26:27], v[50:51], v[58:59]
	v_pk_fma_f32 v[58:59], s[6:7], v[48:49], v[62:63]
	v_cvt_pk_bf16_f32 v48, v52, v53
	v_cvt_pk_bf16_f32 v49, v54, v55
	v_cvt_pk_bf16_f32 v50, v58, v59
	v_cvt_pk_bf16_f32 v51, v56, v57
	global_store_dwordx4 v[70:71], v[48:51], off offset:256
	s_nop 1
	v_mul_f32_e32 v48, v53, v53
	v_mul_f32_e32 v49, v55, v55
	v_fmac_f32_e32 v48, v52, v52
	v_fmac_f32_e32 v49, v54, v54
	v_add_f32_e32 v48, v48, v49
	v_mul_f32_e32 v49, v59, v59
	v_fmac_f32_e32 v49, v58, v58
	v_add_f32_e32 v48, v49, v48
	v_mul_f32_e32 v49, v57, v57
	v_fmac_f32_e32 v49, v56, v56
	v_add_f32_e32 v48, v49, v48
	v_add_f32_e32 v48, v66, v48
	ds_bpermute_b32 v49, v153, v48
	s_waitcnt lgkmcnt(0)
	v_add_f32_e32 v48, v48, v49
	ds_bpermute_b32 v49, v152, v48
	s_and_saveexec_b64 s[40:41], vcc
	s_cbranch_execz .LBB0_1595
	v_lshlrev_b64 v[50:51], 6, v[64:65]
	v_lshl_add_u64 v[50:51], s[20:21], 0, v[50:51]
	v_lshl_add_u64 v[50:51], s[38:39], 2, v[50:51]
	s_lshl_b32 s78, s44, 2
	s_mov_b32 s79, s31
	v_lshl_add_u64 v[50:51], v[50:51], 0, s[78:79]
	s_waitcnt lgkmcnt(0)
	v_add_f32_e32 v48, v48, v49
	global_store_dword v[50:51], v48, off
; __device__ __forceinline__ u32x4 pack8(const f32x4& a, const f32x4& b) { u32x4 w; w.x = pk2(a[0], a[1]); w.y = pk2(a[2], a[3]); w.z = pk2(b[0], b[1]); w.w = pk2(b[2], b[3]); return w; }
;     __device__ __forceinline__ void operator()(const f32x4 (&acc)[2][2][4][2], const pg8::Unit& u, int wr, int wc, int fr, int fq) const { asm volatile("" : "+v"(fr), "+v"(fq));
;     ...
;         for (int am_ = 0; am_ < 8; ++am_) { const int ai = am_ >> 2, m = am_ & 3; const int row = u.pm * 256 + ai * 128 + wr * 64 + m * 16 + fr; float sq = 0.f;
; #pragma unroll
;             for (int bj = 0; bj < 2; ++bj) { const int col0 = u.pn * 256 + bj * 128 + wc * 32 + 8 * fq; bf16_t* xp = xb + (size_t)row * D + col0; const u32x4 o = *(const u32x4*)xp;
;                 f32x4 x0 = {bflo(o.x), bfhi(o.x), bflo(o.y), bfhi(o.y)}, x1 = {bflo(o.z), bfhi(o.z), bflo(o.w), bfhi(o.w)}; x0 += acc[ai][bj][m][0] * scale; x1 += acc[ai][bj][m][1] * scale;
;                 *(u32x4*)xp = pack8(x0, x1);
;                 sq += (x0[0] * x0[0] + x0[1] * x0[1]) + (x0[2] * x0[2] + x0[3] * x0[3]) + (x1[0] * x1[0] + x1[1] * x1[1]) + (x1[2] * x1[2] + x1[3] * x1[3]); }
;             sq += __shfl_xor(sq, 16); sq += __shfl_xor(sq, 32);
;             if (fq == 0) ssn[(size_t)row * 16 + u.pn * 4 + wc] = sq; }
.LBB0_1595:
	s_or_b64 exec, exec, s[40:41]
	v_add_u32_e32 v48, 0x90, v144
	s_waitcnt lgkmcnt(0)
	v_ashrrev_i32_e32 v49, 31, v48
	v_lshlrev_b64 v[50:51], 11, v[48:49]
	v_lshl_add_u64 v[50:51], s[86:87], 0, v[50:51]
	v_lshl_add_u64 v[54:55], v[142:143], 1, v[50:51]
	s_waitcnt vmcnt(15)
	v_mov_b32_e32 v50, v212
	v_mov_b32_e32 v51, v213
	v_mov_b32_e32 v52, v214
	v_mov_b32_e32 v53, v215
	v_lshlrev_b32_e32 v56, 16, v50
	v_and_b32_e32 v57, 0xffff0000, v50
	v_lshlrev_b32_e32 v50, 16, v51
	v_and_b32_e32 v51, 0xffff0000, v51
	v_lshlrev_b32_e32 v58, 16, v52
	v_and_b32_e32 v59, 0xffff0000, v52
	v_lshlrev_b32_e32 v52, 16, v53
	v_and_b32_e32 v53, 0xffff0000, v53
	v_pk_fma_f32 v[46:47], s[26:27], v[46:47], v[50:51]
	v_pk_fma_f32 v[44:45], s[6:7], v[44:45], v[56:57]
	v_pk_fma_f32 v[50:51], s[26:27], v[42:43], v[52:53]
	v_pk_fma_f32 v[52:53], s[6:7], v[40:41], v[58:59]
	v_cvt_pk_bf16_f32 v40, v44, v45
	v_cvt_pk_bf16_f32 v41, v46, v47
	v_cvt_pk_bf16_f32 v42, v52, v53
	v_cvt_pk_bf16_f32 v43, v50, v51
	global_store_dwordx4 v[54:55], v[40:43], off
	s_nop 1
	v_mul_f32_e32 v40, v45, v45
	v_mul_f32_e32 v41, v47, v47
	v_fmac_f32_e32 v40, v44, v44
	v_fmac_f32_e32 v41, v46, v46
	v_add_f32_e32 v40, v40, v41
	v_mul_f32_e32 v41, v53, v53
	v_fmac_f32_e32 v41, v52, v52
	v_add_f32_e32 v40, v41, v40
	v_mul_f32_e32 v41, v51, v51
	v_fmac_f32_e32 v41, v50, v50
	v_add_f32_e32 v50, v41, v40
	s_waitcnt vmcnt(15)
	v_mov_b32_e32 v40, v216
	v_mov_b32_e32 v41, v217
	v_mov_b32_e32 v42, v218
	v_mov_b32_e32 v43, v219
	v_lshlrev_b32_e32 v44, 16, v40
	v_and_b32_e32 v45, 0xffff0000, v40
	v_lshlrev_b32_e32 v40, 16, v41
	v_and_b32_e32 v41, 0xffff0000, v41
	v_lshlrev_b32_e32 v46, 16, v42
	v_and_b32_e32 v47, 0xffff0000, v42
	v_lshlrev_b32_e32 v42, 16, v43
	v_and_b32_e32 v43, 0xffff0000, v43
	v_pk_fma_f32 v[38:39], s[26:27], v[38:39], v[40:41]
	v_pk_fma_f32 v[36:37], s[6:7], v[36:37], v[44:45]
	v_pk_fma_f32 v[40:41], s[26:27], v[34:35], v[42:43]
	v_pk_fma_f32 v[42:43], s[6:7], v[32:33], v[46:47]
	v_cvt_pk_bf16_f32 v32, v36, v37
	v_cvt_pk_bf16_f32 v33, v38, v39
	v_cvt_pk_bf16_f32 v34, v42, v43
	v_cvt_pk_bf16_f32 v35, v40, v41
	global_store_dwordx4 v[54:55], v[32:35], off offset:256
	s_nop 1
	v_mul_f32_e32 v32, v37, v37
	v_mul_f32_e32 v33, v39, v39
	v_fmac_f32_e32 v32, v36, v36
	v_fmac_f32_e32 v33, v38, v38
	v_add_f32_e32 v32, v32, v33
	v_mul_f32_e32 v33, v43, v43
	v_fmac_f32_e32 v33, v42, v42
	v_add_f32_e32 v32, v33, v32
	v_mul_f32_e32 v33, v41, v41
	v_fmac_f32_e32 v33, v40, v40
	v_add_f32_e32 v32, v33, v32
	v_add_f32_e32 v32, v50, v32
	ds_bpermute_b32 v33, v153, v32
	s_waitcnt lgkmcnt(0)
	v_add_f32_e32 v32, v32, v33
	ds_bpermute_b32 v33, v152, v32
	s_and_saveexec_b64 s[40:41], vcc
	s_cbranch_execz .LBB0_1597
	v_lshlrev_b64 v[34:35], 6, v[48:49]
	v_lshl_add_u64 v[34:35], s[20:21], 0, v[34:35]
	v_lshl_add_u64 v[34:35], s[38:39], 2, v[34:35]
	s_lshl_b32 s78, s44, 2
	s_mov_b32 s79, s31
	v_lshl_add_u64 v[34:35], v[34:35], 0, s[78:79]
	s_waitcnt lgkmcnt(0)
	v_add_f32_e32 v32, v32, v33
	global_store_dword v[34:35], v32, off
; __device__ __forceinline__ u32x4 pack8(const f32x4& a, const f32x4& b) { u32x4 w; w.x = pk2(a[0], a[1]); w.y = pk2(a[2], a[3]); w.z = pk2(b[0], b[1]); w.w = pk2(b[2], b[3]); return w; }
;     __device__ __forceinline__ void operator()(const f32x4 (&acc)[2][2][4][2], const pg8::Unit& u, int wr, int wc, int fr, int fq) const { asm volatile("" : "+v"(fr), "+v"(fq));
;     ...
;         for (int am_ = 0; am_ < 8; ++am_) { const int ai = am_ >> 2, m = am_ & 3; const int row = u.pm * 256 + ai * 128 + wr * 64 + m * 16 + fr; float sq = 0.f;
; #pragma unroll
;             for (int bj = 0; bj < 2; ++bj) { const int col0 = u.pn * 256 + bj * 128 + wc * 32 + 8 * fq; bf16_t* xp = xb + (size_t)row * D + col0; const u32x4 o = *(const u32x4*)xp;
;                 f32x4 x0 = {bflo(o.x), bfhi(o.x), bflo(o.y), bfhi(o.y)}, x1 = {bflo(o.z), bfhi(o.z), bflo(o.w), bfhi(o.w)}; x0 += acc[ai][bj][m][0] * scale; x1 += acc[ai][bj][m][1] * scale;
;                 *(u32x4*)xp = pack8(x0, x1);
;                 sq += (x0[0] * x0[0] + x0[1] * x0[1]) + (x0[2] * x0[2] + x0[3] * x0[3]) + (x1[0] * x1[0] + x1[1] * x1[1]) + (x1[2] * x1[2] + x1[3] * x1[3]); }
;             sq += __shfl_xor(sq, 16); sq += __shfl_xor(sq, 32);
;             if (fq == 0) ssn[(size_t)row * 16 + u.pn * 4 + wc] = sq; }
.LBB0_1597:
	s_or_b64 exec, exec, s[40:41]
	v_add_u32_e32 v32, 0xa0, v144
	s_waitcnt lgkmcnt(0)
	v_ashrrev_i32_e32 v33, 31, v32
	v_lshlrev_b64 v[34:35], 11, v[32:33]
	v_lshl_add_u64 v[34:35], s[86:87], 0, v[34:35]
	v_lshl_add_u64 v[38:39], v[142:143], 1, v[34:35]
	s_waitcnt vmcnt(15)
	v_mov_b32_e32 v34, v220
	v_mov_b32_e32 v35, v221
	v_mov_b32_e32 v36, v222
	v_mov_b32_e32 v37, v223
	v_lshlrev_b32_e32 v40, 16, v34
	v_and_b32_e32 v41, 0xffff0000, v34
	v_lshlrev_b32_e32 v34, 16, v35
	v_and_b32_e32 v35, 0xffff0000, v35
	v_lshlrev_b32_e32 v42, 16, v36
	v_and_b32_e32 v43, 0xffff0000, v36
	v_lshlrev_b32_e32 v36, 16, v37
	v_and_b32_e32 v37, 0xffff0000, v37
	v_pk_fma_f32 v[30:31], s[26:27], v[30:31], v[34:35]
	v_pk_fma_f32 v[28:29], s[6:7], v[28:29], v[40:41]
	v_pk_fma_f32 v[34:35], s[26:27], v[26:27], v[36:37]
	v_pk_fma_f32 v[36:37], s[6:7], v[24:25], v[42:43]
	v_cvt_pk_bf16_f32 v24, v28, v29
	v_cvt_pk_bf16_f32 v25, v30, v31
	v_cvt_pk_bf16_f32 v26, v36, v37
	v_cvt_pk_bf16_f32 v27, v34, v35
	global_store_dwordx4 v[38:39], v[24:27], off
	s_nop 1
	v_mul_f32_e32 v24, v29, v29
	v_mul_f32_e32 v25, v31, v31
	v_fmac_f32_e32 v24, v28, v28
	v_fmac_f32_e32 v25, v30, v30
	v_add_f32_e32 v24, v24, v25
	v_mul_f32_e32 v25, v37, v37
	v_fmac_f32_e32 v25, v36, v36
	v_add_f32_e32 v24, v25, v24
	v_mul_f32_e32 v25, v35, v35
	v_fmac_f32_e32 v25, v34, v34
	v_add_f32_e32 v34, v25, v24
	s_waitcnt vmcnt(15)
	v_mov_b32_e32 v24, v224
	v_mov_b32_e32 v25, v225
	v_mov_b32_e32 v26, v226
	v_mov_b32_e32 v27, v227
	v_lshlrev_b32_e32 v28, 16, v24
	v_and_b32_e32 v29, 0xffff0000, v24
	v_lshlrev_b32_e32 v24, 16, v25
	v_and_b32_e32 v25, 0xffff0000, v25
	v_lshlrev_b32_e32 v30, 16, v26
	v_and_b32_e32 v31, 0xffff0000, v26
	v_lshlrev_b32_e32 v26, 16, v27
	v_and_b32_e32 v27, 0xffff0000, v27
	v_pk_fma_f32 v[22:23], s[26:27], v[22:23], v[24:25]
	v_pk_fma_f32 v[20:21], s[6:7], v[20:21], v[28:29]
	v_pk_fma_f32 v[24:25], s[26:27], v[18:19], v[26:27]
	v_pk_fma_f32 v[26:27], s[6:7], v[16:17], v[30:31]
	v_cvt_pk_bf16_f32 v16, v20, v21
	v_cvt_pk_bf16_f32 v17, v22, v23
	v_cvt_pk_bf16_f32 v18, v26, v27
	v_cvt_pk_bf16_f32 v19, v24, v25
	global_store_dwordx4 v[38:39], v[16:19], off offset:256
	s_nop 1
	v_mul_f32_e32 v16, v21, v21
	v_mul_f32_e32 v17, v23, v23
	v_fmac_f32_e32 v16, v20, v20
	v_fmac_f32_e32 v17, v22, v22
	v_add_f32_e32 v16, v16, v17
	v_mul_f32_e32 v17, v27, v27
	v_fmac_f32_e32 v17, v26, v26
	v_add_f32_e32 v16, v17, v16
	v_mul_f32_e32 v17, v25, v25
	v_fmac_f32_e32 v17, v24, v24
	v_add_f32_e32 v16, v17, v16
	v_add_f32_e32 v16, v34, v16
	ds_bpermute_b32 v17, v153, v16
	s_waitcnt lgkmcnt(0)
	v_add_f32_e32 v16, v16, v17
	ds_bpermute_b32 v17, v152, v16
	s_and_saveexec_b64 s[40:41], vcc
	s_cbranch_execz .LBB0_1599
	v_lshlrev_b64 v[18:19], 6, v[32:33]
	v_lshl_add_u64 v[18:19], s[20:21], 0, v[18:19]
	v_lshl_add_u64 v[18:19], s[38:39], 2, v[18:19]
	s_lshl_b32 s78, s44, 2
	s_mov_b32 s79, s31
	v_lshl_add_u64 v[18:19], v[18:19], 0, s[78:79]
	s_waitcnt lgkmcnt(0)
	v_add_f32_e32 v16, v16, v17
	global_store_dword v[18:19], v16, off
.LBB0_1599:
	s_or_b64 exec, exec, s[40:41]
	v_add_u32_e32 v16, 0xb0, v144
	s_waitcnt lgkmcnt(0)
	v_ashrrev_i32_e32 v17, 31, v16
	v_lshlrev_b64 v[18:19], 11, v[16:17]
	v_lshl_add_u64 v[18:19], s[86:87], 0, v[18:19]
	v_lshl_add_u64 v[22:23], v[142:143], 1, v[18:19]
	s_waitcnt vmcnt(15)
	v_mov_b32_e32 v18, v234
	v_mov_b32_e32 v19, v235
	v_mov_b32_e32 v20, v236
	v_mov_b32_e32 v21, v237
	v_lshlrev_b32_e32 v24, 16, v18
	v_and_b32_e32 v25, 0xffff0000, v18
	v_lshlrev_b32_e32 v18, 16, v19
	v_and_b32_e32 v19, 0xffff0000, v19
	v_lshlrev_b32_e32 v26, 16, v20
	v_and_b32_e32 v27, 0xffff0000, v20
	v_lshlrev_b32_e32 v20, 16, v21
	v_and_b32_e32 v21, 0xffff0000, v21
	v_pk_fma_f32 v[14:15], s[26:27], v[14:15], v[18:19]
	v_pk_fma_f32 v[12:13], s[6:7], v[12:13], v[24:25]
	v_pk_fma_f32 v[18:19], s[26:27], v[10:11], v[20:21]
	v_pk_fma_f32 v[20:21], s[6:7], v[8:9], v[26:27]
	v_cvt_pk_bf16_f32 v8, v12, v13
	v_cvt_pk_bf16_f32 v9, v14, v15
	v_cvt_pk_bf16_f32 v10, v20, v21
	v_cvt_pk_bf16_f32 v11, v18, v19
	global_store_dwordx4 v[22:23], v[8:11], off
	s_nop 1
	v_mul_f32_e32 v8, v13, v13
	v_mul_f32_e32 v9, v15, v15
	v_fmac_f32_e32 v8, v12, v12
	v_fmac_f32_e32 v9, v14, v14
	v_add_f32_e32 v8, v8, v9
	v_mul_f32_e32 v9, v21, v21
	v_fmac_f32_e32 v9, v20, v20
	v_add_f32_e32 v8, v9, v8
	v_mul_f32_e32 v9, v19, v19
	v_fmac_f32_e32 v9, v18, v18
	v_add_f32_e32 v18, v9, v8
	s_waitcnt vmcnt(15)
	v_mov_b32_e32 v8, v238
	v_mov_b32_e32 v9, v239
	v_mov_b32_e32 v10, v240
	v_mov_b32_e32 v11, v241
	v_lshlrev_b32_e32 v12, 16, v8
	v_and_b32_e32 v13, 0xffff0000, v8
	v_lshlrev_b32_e32 v8, 16, v9
	v_and_b32_e32 v9, 0xffff0000, v9
	v_lshlrev_b32_e32 v14, 16, v10
	v_and_b32_e32 v15, 0xffff0000, v10
	v_lshlrev_b32_e32 v10, 16, v11
	v_and_b32_e32 v11, 0xffff0000, v11
	v_pk_fma_f32 v[6:7], s[26:27], v[6:7], v[8:9]
	v_pk_fma_f32 v[4:5], s[6:7], v[4:5], v[12:13]
	v_pk_fma_f32 v[8:9], s[26:27], v[2:3], v[10:11]
	v_pk_fma_f32 v[10:11], s[6:7], v[0:1], v[14:15]
	v_cvt_pk_bf16_f32 v0, v4, v5
	v_cvt_pk_bf16_f32 v1, v6, v7
	v_cvt_pk_bf16_f32 v2, v10, v11
	v_cvt_pk_bf16_f32 v3, v8, v9
	global_store_dwordx4 v[22:23], v[0:3], off offset:256
	s_nop 1
	v_mul_f32_e32 v0, v5, v5
	v_mul_f32_e32 v1, v7, v7
	v_fmac_f32_e32 v0, v4, v4
	v_fmac_f32_e32 v1, v6, v6
	v_add_f32_e32 v0, v0, v1
	v_mul_f32_e32 v1, v11, v11
	v_fmac_f32_e32 v1, v10, v10
	v_add_f32_e32 v0, v1, v0
	v_mul_f32_e32 v1, v9, v9
	v_fmac_f32_e32 v1, v8, v8
	v_add_f32_e32 v0, v1, v0
	v_add_f32_e32 v0, v18, v0
	ds_bpermute_b32 v1, v153, v0
	s_waitcnt lgkmcnt(0)
	v_add_f32_e32 v0, v0, v1
	ds_bpermute_b32 v1, v152, v0
	s_and_saveexec_b64 s[40:41], vcc
	s_cbranch_execz .LBB0_1601
	v_lshlrev_b64 v[2:3], 6, v[16:17]
	v_lshl_add_u64 v[2:3], s[20:21], 0, v[2:3]
	v_lshl_add_u64 v[2:3], s[38:39], 2, v[2:3]
	s_lshl_b32 s38, s44, 2
	s_mov_b32 s39, s31
	v_lshl_add_u64 v[2:3], v[2:3], 0, s[38:39]
	s_waitcnt lgkmcnt(0)
	v_add_f32_e32 v0, v0, v1
	global_store_dword v[2:3], v0, off

; __global__ void __launch_bounds__(512, 2) mega_fwd(Args a_unused) {
	.amdhsa_kernel _Z8mega_fwd4Args
		.amdhsa_group_segment_fixed_size 0
		.amdhsa_private_segment_fixed_size 0
		.amdhsa_kernarg_size 576
		.amdhsa_user_sgpr_count 2
		.amdhsa_user_sgpr_dispatch_ptr 0
		.amdhsa_user_sgpr_queue_ptr 0
		.amdhsa_user_sgpr_kernarg_segment_ptr 1
		.amdhsa_user_sgpr_dispatch_id 0
		.amdhsa_user_sgpr_kernarg_preload_length 0
		.amdhsa_user_sgpr_kernarg_preload_offset 0
		.amdhsa_user_sgpr_private_segment_size 0
		.amdhsa_uses_dynamic_stack 0
		.amdhsa_enable_private_segment 0
		.amdhsa_system_sgpr_workgroup_id_x 1
		.amdhsa_system_sgpr_workgroup_id_y 0
		.amdhsa_system_sgpr_workgroup_id_z 0
		.amdhsa_system_sgpr_workgroup_info 0
		.amdhsa_system_vgpr_workitem_id 2
		.amdhsa_next_free_vgpr 256
		.amdhsa_next_free_sgpr 102
		.amdhsa_accum_offset 256
		.amdhsa_reserve_vcc 1
		.amdhsa_float_round_mode_32 0
		.amdhsa_float_round_mode_16_64 0
		.amdhsa_float_denorm_mode_32 3
		.amdhsa_float_denorm_mode_16_64 3
		.amdhsa_dx10_clamp 1
		.amdhsa_ieee_mode 1
		.amdhsa_fp16_overflow 0
		.amdhsa_tg_split 0
		.amdhsa_exception_fp_ieee_invalid_op 0
		.amdhsa_exception_fp_denorm_src 0
		.amdhsa_exception_fp_ieee_div_zero 0
		.amdhsa_exception_fp_ieee_overflow 0
		.amdhsa_exception_fp_ieee_underflow 0
		.amdhsa_exception_fp_ieee_inexact 0
		.amdhsa_exception_int_div_zero 0
	.end_amdhsa_kernel
